# GEMM K-loops: first trip after an epilogue uses counted vmcnt(24/40) in phases 1-2 so the mainloop starts while the epilogue stores drain
# speedup vs baseline: 1.0047x; 1.0047x over previous
.LBB0_205:
	s_mov_b32 s98, 0
	s_cmp_lt_i32 s34, 2
	s_cselect_b64 s[6:7], -1, 0
	s_and_b64 s[8:9], s[6:7], s[4:5]
	s_andn2_b64 vcc, exec, s[8:9]
	s_cbranch_vccnz .LBB0_328
	s_add_i32 s6, 0, 0x22800
	v_lshl_add_u32 v1, v0, 2, s6
	s_add_u32 s6, s38, 0x1300000
	s_addc_u32 s7, s39, 0
	s_cmpk_lt_i32 s2, 0x400
	s_movk_i32 s4, 0x100
	s_cselect_b64 s[10:11], -1, 0
	v_cmp_gt_u32_e64 s[4:5], s4, v0
	s_and_b64 vcc, exec, s[10:11]
	s_cbranch_vccz .LBB0_214
	s_ashr_i32 s12, s2, 31
	s_lshr_b32 s12, s12, 29
	s_add_i32 s14, s2, s12
	s_and_b32 s12, s14, -8
	s_sub_i32 s18, s2, s12
	s_cmp_gt_i32 s18, -1
	s_cbranch_scc0 .LBB0_209
	s_lshl_b32 s15, s18, 7
	s_cbranch_execz .LBB0_210
	s_branch .LBB0_211

.LBB0_289:
	ds_read_b128 v[148:151], v165
	ds_read_b128 v[152:155], v165 offset:1024
	ds_read_b128 v[156:159], v165 offset:2048
	ds_read_b128 v[168:171], v165 offset:3072
	ds_read_b128 v[172:175], v166
	ds_read_b128 v[176:179], v166 offset:1024
	ds_read_b128 v[180:183], v166 offset:2048
	ds_read_b128 v[184:187], v166 offset:3072
	s_add_u32 s54, s52, 0xfffc0080
	s_addc_u32 s55, s53, -1
	s_cmp_eq_u32 s85, 12
	s_cselect_b32 s57, s29, s55
	s_cselect_b32 s56, s81, s54
	s_cselect_b32 s55, s27, s84
	s_cselect_b32 s54, s82, s83
	v_lshl_add_u64 v[160:161], s[52:53], 0, v[140:141]
	s_add_i32 m0, s51, 0xc000
	ds_read_b128 v[188:191], v167
	ds_read_b128 v[192:195], v167 offset:1024
	ds_read_b128 v[200:203], v167 offset:2048
	ds_read_b128 v[204:207], v167 offset:3072
	ds_read_b128 v[208:211], v167 offset:4096
	ds_read_b128 v[212:215], v167 offset:5120
	ds_read_b128 v[216:219], v167 offset:6144
	ds_read_b128 v[220:223], v167 offset:7168
	global_load_lds_dwordx4 v[160:161], off
	v_lshl_add_u64 v[160:161], s[52:53], 0, v[142:143]
	s_add_i32 m0, s51, 0xe000
	s_nop 0
	global_load_lds_dwordx4 v[160:161], off
	s_cmp_eq_u32 s98, 0
	s_cbranch_scc1 .Lrw_strict_p1_0
	s_waitcnt vmcnt(24)
	s_branch .Lrw_done_p1_0
.Lrw_strict_p1_0:
	s_waitcnt vmcnt(8)
.Lrw_done_p1_0:
	s_waitcnt lgkmcnt(0)
	s_barrier
	s_setprio 1
	s_waitcnt lgkmcnt(0)
	v_mfma_f32_16x16x32_bf16 v[126:129], v[148:151], v[188:191], v[126:129]
	v_mfma_f32_16x16x32_bf16 v[122:125], v[156:159], v[188:191], v[122:125]
	v_mfma_f32_16x16x32_bf16 v[110:113], v[148:151], v[200:203], v[110:113]
	v_mfma_f32_16x16x32_bf16 v[106:109], v[156:159], v[200:203], v[106:109]
	v_mfma_f32_16x16x32_bf16 v[94:97], v[148:151], v[208:211], v[94:97]
	v_mfma_f32_16x16x32_bf16 v[90:93], v[156:159], v[208:211], v[90:93]
	v_mfma_f32_16x16x32_bf16 v[78:81], v[148:151], v[216:219], v[78:81]
	v_mfma_f32_16x16x32_bf16 v[74:77], v[156:159], v[216:219], v[74:77]
	v_mfma_f32_16x16x32_bf16 v[126:129], v[152:155], v[192:195], v[126:129]
	v_mfma_f32_16x16x32_bf16 v[122:125], v[168:171], v[192:195], v[122:125]
	v_mfma_f32_16x16x32_bf16 v[110:113], v[152:155], v[204:207], v[110:113]
	v_mfma_f32_16x16x32_bf16 v[106:109], v[168:171], v[204:207], v[106:109]
	v_mfma_f32_16x16x32_bf16 v[94:97], v[152:155], v[212:215], v[94:97]
	v_mfma_f32_16x16x32_bf16 v[90:93], v[168:171], v[212:215], v[90:93]
	v_mfma_f32_16x16x32_bf16 v[78:81], v[152:155], v[220:223], v[78:81]
	v_mfma_f32_16x16x32_bf16 v[74:77], v[168:171], v[220:223], v[74:77]
	s_setprio 0
	s_setprio 1
	v_mfma_f32_16x16x32_bf16 v[118:121], v[172:175], v[188:191], v[118:121]
	v_mfma_f32_16x16x32_bf16 v[114:117], v[180:183], v[188:191], v[114:117]
	v_mfma_f32_16x16x32_bf16 v[102:105], v[172:175], v[200:203], v[102:105]
	v_mfma_f32_16x16x32_bf16 v[98:101], v[180:183], v[200:203], v[98:101]
	v_mfma_f32_16x16x32_bf16 v[86:89], v[172:175], v[208:211], v[86:89]
	v_mfma_f32_16x16x32_bf16 v[82:85], v[180:183], v[208:211], v[82:85]
	v_mfma_f32_16x16x32_bf16 v[70:73], v[172:175], v[216:219], v[70:73]
	v_mfma_f32_16x16x32_bf16 v[66:69], v[180:183], v[216:219], v[66:69]
	v_mfma_f32_16x16x32_bf16 v[118:121], v[176:179], v[192:195], v[118:121]
	v_mfma_f32_16x16x32_bf16 v[114:117], v[184:187], v[192:195], v[114:117]
	v_mfma_f32_16x16x32_bf16 v[102:105], v[176:179], v[204:207], v[102:105]
	v_mfma_f32_16x16x32_bf16 v[98:101], v[184:187], v[204:207], v[98:101]
	v_mfma_f32_16x16x32_bf16 v[86:89], v[176:179], v[212:215], v[86:89]
	v_mfma_f32_16x16x32_bf16 v[82:85], v[184:187], v[212:215], v[82:85]
	v_mfma_f32_16x16x32_bf16 v[70:73], v[176:179], v[220:223], v[70:73]
	v_mfma_f32_16x16x32_bf16 v[66:69], v[184:187], v[220:223], v[66:69]
	s_setprio 0
	s_barrier
	s_add_i32 s86, s74, s64
	v_lshl_add_u64 v[160:161], s[54:55], 0, v[132:133]
	s_mov_b32 m0, s86
	ds_read_b128 v[188:191], v167 offset:16384
	ds_read_b128 v[192:195], v167 offset:17408
	ds_read_b128 v[200:203], v167 offset:18432
	ds_read_b128 v[204:207], v167 offset:19456
	ds_read_b128 v[208:211], v167 offset:20480
	ds_read_b128 v[212:215], v167 offset:21504
	ds_read_b128 v[216:219], v167 offset:22528
	ds_read_b128 v[220:223], v167 offset:23552
	global_load_lds_dwordx4 v[160:161], off
	s_add_i32 m0, s86, 0x2000
	s_add_u32 s86, s54, 0x40000
	v_lshl_add_u64 v[196:197], s[54:55], 0, v[136:137]
	s_addc_u32 s87, s55, 0
	s_add_i32 s88, s75, s64
	global_load_lds_dwordx4 v[196:197], off
	v_lshl_add_u64 v[224:225], s[86:87], 0, v[132:133]
	s_mov_b32 m0, s88
	v_lshl_add_u64 v[226:227], s[56:57], 0, v[134:135]
	global_load_lds_dwordx4 v[224:225], off
	v_lshl_add_u64 v[224:225], s[86:87], 0, v[136:137]
	s_add_i32 m0, s88, 0x2000
	s_nop 0
	global_load_lds_dwordx4 v[224:225], off
	v_lshl_add_u64 v[224:225], s[56:57], 0, v[130:131]
	s_mov_b32 m0, s51
	s_nop 0
	global_load_lds_dwordx4 v[224:225], off
	s_mov_b32 m0, s65
	s_nop 0
	global_load_lds_dwordx4 v[226:227], off
	s_cmp_eq_u32 s98, 0
	s_cbranch_scc1 .Lrw_strict_p1_1
	s_waitcnt vmcnt(24)
	s_branch .Lrw_done_p1_1

.Lrw_done_p1_1:
	s_mov_b32 s98, 0
	s_waitcnt lgkmcnt(0)
	s_barrier
	s_setprio 1
	s_waitcnt lgkmcnt(0)
	v_mfma_f32_16x16x32_bf16 v[62:65], v[148:151], v[188:191], v[62:65]
	v_mfma_f32_16x16x32_bf16 v[58:61], v[156:159], v[188:191], v[58:61]
	v_mfma_f32_16x16x32_bf16 v[46:49], v[148:151], v[200:203], v[46:49]
	v_mfma_f32_16x16x32_bf16 v[42:45], v[156:159], v[200:203], v[42:45]
	v_mfma_f32_16x16x32_bf16 v[30:33], v[148:151], v[208:211], v[30:33]
	v_mfma_f32_16x16x32_bf16 v[26:29], v[156:159], v[208:211], v[26:29]
	v_mfma_f32_16x16x32_bf16 v[14:17], v[148:151], v[216:219], v[14:17]
	v_mfma_f32_16x16x32_bf16 v[10:13], v[156:159], v[216:219], v[10:13]
	v_mfma_f32_16x16x32_bf16 v[62:65], v[152:155], v[192:195], v[62:65]
	v_mfma_f32_16x16x32_bf16 v[58:61], v[168:171], v[192:195], v[58:61]
	v_mfma_f32_16x16x32_bf16 v[46:49], v[152:155], v[204:207], v[46:49]
	v_mfma_f32_16x16x32_bf16 v[42:45], v[168:171], v[204:207], v[42:45]
	v_mfma_f32_16x16x32_bf16 v[30:33], v[152:155], v[212:215], v[30:33]
	v_mfma_f32_16x16x32_bf16 v[26:29], v[168:171], v[212:215], v[26:29]
	v_mfma_f32_16x16x32_bf16 v[14:17], v[152:155], v[220:223], v[14:17]
	v_mfma_f32_16x16x32_bf16 v[10:13], v[168:171], v[220:223], v[10:13]
	s_setprio 0
	s_setprio 1
	v_mfma_f32_16x16x32_bf16 v[54:57], v[172:175], v[188:191], v[54:57]
	v_mfma_f32_16x16x32_bf16 v[50:53], v[180:183], v[188:191], v[50:53]
	v_mfma_f32_16x16x32_bf16 v[38:41], v[172:175], v[200:203], v[38:41]
	v_mfma_f32_16x16x32_bf16 v[34:37], v[180:183], v[200:203], v[34:37]
	v_mfma_f32_16x16x32_bf16 v[22:25], v[172:175], v[208:211], v[22:25]
	v_mfma_f32_16x16x32_bf16 v[18:21], v[180:183], v[208:211], v[18:21]
	v_mfma_f32_16x16x32_bf16 v[6:9], v[172:175], v[216:219], v[6:9]
	v_mfma_f32_16x16x32_bf16 v[2:5], v[180:183], v[216:219], v[2:5]
	v_mfma_f32_16x16x32_bf16 v[54:57], v[176:179], v[192:195], v[54:57]
	v_mfma_f32_16x16x32_bf16 v[50:53], v[184:187], v[192:195], v[50:53]
	v_mfma_f32_16x16x32_bf16 v[38:41], v[176:179], v[204:207], v[38:41]
	v_mfma_f32_16x16x32_bf16 v[34:37], v[184:187], v[204:207], v[34:37]
	v_mfma_f32_16x16x32_bf16 v[22:25], v[176:179], v[212:215], v[22:25]
	v_mfma_f32_16x16x32_bf16 v[18:21], v[184:187], v[212:215], v[18:21]
	v_mfma_f32_16x16x32_bf16 v[6:9], v[176:179], v[220:223], v[6:9]
	v_mfma_f32_16x16x32_bf16 v[2:5], v[184:187], v[220:223], v[2:5]
	s_setprio 0
	s_barrier
	s_add_i32 s86, 0, 0x18000
	v_add_u32_e32 v138, s86, v162
	s_add_i32 s87, 0, 0x1c000
	ds_read_b128 v[148:151], v138
	ds_read_b128 v[152:155], v138 offset:1024
	ds_read_b128 v[156:159], v138 offset:2048
	ds_read_b128 v[168:171], v138 offset:3072
	v_add_u32_e32 v138, s87, v162
	ds_read_b128 v[172:175], v138
	ds_read_b128 v[176:179], v138 offset:1024
	ds_read_b128 v[180:183], v138 offset:2048
	ds_read_b128 v[184:187], v138 offset:3072
	s_add_u32 s56, s56, 0x40000
	s_addc_u32 s57, s57, 0
	s_mov_b32 m0, s66
	v_lshl_add_u64 v[228:229], s[56:57], 0, v[130:131]
	ds_read_b128 v[188:191], v167 offset:32768
	ds_read_b128 v[192:195], v167 offset:33792
	ds_read_b128 v[200:203], v167 offset:34816
	ds_read_b128 v[204:207], v167 offset:35840
	ds_read_b128 v[208:211], v167 offset:36864
	ds_read_b128 v[212:215], v167 offset:37888
	ds_read_b128 v[216:219], v167 offset:38912
	ds_read_b128 v[220:223], v167 offset:39936
	global_load_lds_dwordx4 v[228:229], off
	v_lshl_add_u64 v[228:229], s[56:57], 0, v[134:135]
	s_mov_b32 m0, s67
	s_nop 0
	global_load_lds_dwordx4 v[228:229], off
	s_waitcnt vmcnt(8)
	s_waitcnt lgkmcnt(0)
	s_barrier
	s_setprio 1
	s_waitcnt lgkmcnt(0)
	v_mfma_f32_16x16x32_bf16 v[126:129], v[148:151], v[188:191], v[126:129]
	v_mfma_f32_16x16x32_bf16 v[122:125], v[156:159], v[188:191], v[122:125]
	v_mfma_f32_16x16x32_bf16 v[110:113], v[148:151], v[200:203], v[110:113]
	v_mfma_f32_16x16x32_bf16 v[106:109], v[156:159], v[200:203], v[106:109]
	v_mfma_f32_16x16x32_bf16 v[94:97], v[148:151], v[208:211], v[94:97]
	v_mfma_f32_16x16x32_bf16 v[90:93], v[156:159], v[208:211], v[90:93]
	v_mfma_f32_16x16x32_bf16 v[78:81], v[148:151], v[216:219], v[78:81]
	v_mfma_f32_16x16x32_bf16 v[74:77], v[156:159], v[216:219], v[74:77]
	v_mfma_f32_16x16x32_bf16 v[126:129], v[152:155], v[192:195], v[126:129]
	v_mfma_f32_16x16x32_bf16 v[122:125], v[168:171], v[192:195], v[122:125]
	v_mfma_f32_16x16x32_bf16 v[110:113], v[152:155], v[204:207], v[110:113]
	v_mfma_f32_16x16x32_bf16 v[106:109], v[168:171], v[204:207], v[106:109]
	v_mfma_f32_16x16x32_bf16 v[94:97], v[152:155], v[212:215], v[94:97]
	v_mfma_f32_16x16x32_bf16 v[90:93], v[168:171], v[212:215], v[90:93]
	v_mfma_f32_16x16x32_bf16 v[78:81], v[152:155], v[220:223], v[78:81]
	v_mfma_f32_16x16x32_bf16 v[74:77], v[168:171], v[220:223], v[74:77]
	s_setprio 0
	s_setprio 1
	v_mfma_f32_16x16x32_bf16 v[118:121], v[172:175], v[188:191], v[118:121]
	v_mfma_f32_16x16x32_bf16 v[114:117], v[180:183], v[188:191], v[114:117]
	v_mfma_f32_16x16x32_bf16 v[102:105], v[172:175], v[200:203], v[102:105]
	v_mfma_f32_16x16x32_bf16 v[98:101], v[180:183], v[200:203], v[98:101]
	v_mfma_f32_16x16x32_bf16 v[86:89], v[172:175], v[208:211], v[86:89]
	v_mfma_f32_16x16x32_bf16 v[82:85], v[180:183], v[208:211], v[82:85]
	v_mfma_f32_16x16x32_bf16 v[70:73], v[172:175], v[216:219], v[70:73]
	v_mfma_f32_16x16x32_bf16 v[66:69], v[180:183], v[216:219], v[66:69]
	v_mfma_f32_16x16x32_bf16 v[118:121], v[176:179], v[192:195], v[118:121]
	v_mfma_f32_16x16x32_bf16 v[114:117], v[184:187], v[192:195], v[114:117]
	v_mfma_f32_16x16x32_bf16 v[102:105], v[176:179], v[204:207], v[102:105]
	v_mfma_f32_16x16x32_bf16 v[98:101], v[184:187], v[204:207], v[98:101]
	v_mfma_f32_16x16x32_bf16 v[86:89], v[176:179], v[212:215], v[86:89]
	v_mfma_f32_16x16x32_bf16 v[82:85], v[184:187], v[212:215], v[82:85]
	v_mfma_f32_16x16x32_bf16 v[70:73], v[176:179], v[220:223], v[70:73]
	v_mfma_f32_16x16x32_bf16 v[66:69], v[184:187], v[220:223], v[66:69]
	s_setprio 0
	s_barrier
	s_add_i32 s56, s86, s64
	v_lshl_add_u64 v[160:161], v[160:161], 0, s[14:15]
	s_mov_b32 m0, s56
	ds_read_b128 v[188:191], v167 offset:49152
	ds_read_b128 v[192:195], v167 offset:50176
	ds_read_b128 v[200:203], v167 offset:51200
	ds_read_b128 v[204:207], v167 offset:52224
	ds_read_b128 v[208:211], v167 offset:53248
	ds_read_b128 v[212:215], v167 offset:54272
	ds_read_b128 v[216:219], v167 offset:55296
	ds_read_b128 v[220:223], v167 offset:56320
	global_load_lds_dwordx4 v[160:161], off
	s_add_i32 m0, s56, 0x2000
	s_add_u32 s54, s54, 0x40080
	v_lshl_add_u64 v[160:161], v[196:197], 0, s[14:15]
	s_addc_u32 s55, s55, 0
	s_add_i32 s56, s87, s64
	global_load_lds_dwordx4 v[160:161], off
	v_lshl_add_u64 v[160:161], s[54:55], 0, v[132:133]
	s_mov_b32 m0, s56
	s_nop 0
	global_load_lds_dwordx4 v[160:161], off
	v_lshl_add_u64 v[160:161], s[54:55], 0, v[136:137]
	s_add_i32 m0, s56, 0x2000
	s_nop 0
	global_load_lds_dwordx4 v[160:161], off
	v_lshl_add_u64 v[160:161], v[224:225], 0, s[14:15]
	s_mov_b32 m0, s68
	s_nop 0
	global_load_lds_dwordx4 v[160:161], off
	v_lshl_add_u64 v[160:161], v[226:227], 0, s[14:15]
	s_mov_b32 m0, s69
	s_nop 0
	global_load_lds_dwordx4 v[160:161], off
	s_waitcnt vmcnt(8)
	s_waitcnt lgkmcnt(0)
	s_barrier
	s_setprio 1
	s_waitcnt lgkmcnt(0)
	v_mfma_f32_16x16x32_bf16 v[62:65], v[148:151], v[188:191], v[62:65]
	v_mfma_f32_16x16x32_bf16 v[58:61], v[156:159], v[188:191], v[58:61]
	v_mfma_f32_16x16x32_bf16 v[46:49], v[148:151], v[200:203], v[46:49]
	v_mfma_f32_16x16x32_bf16 v[42:45], v[156:159], v[200:203], v[42:45]
	v_mfma_f32_16x16x32_bf16 v[30:33], v[148:151], v[208:211], v[30:33]
	v_mfma_f32_16x16x32_bf16 v[26:29], v[156:159], v[208:211], v[26:29]
	v_mfma_f32_16x16x32_bf16 v[14:17], v[148:151], v[216:219], v[14:17]
	v_mfma_f32_16x16x32_bf16 v[10:13], v[156:159], v[216:219], v[10:13]
	v_mfma_f32_16x16x32_bf16 v[62:65], v[152:155], v[192:195], v[62:65]
	v_mfma_f32_16x16x32_bf16 v[58:61], v[168:171], v[192:195], v[58:61]
	v_mfma_f32_16x16x32_bf16 v[46:49], v[152:155], v[204:207], v[46:49]
	v_mfma_f32_16x16x32_bf16 v[42:45], v[168:171], v[204:207], v[42:45]
	v_mfma_f32_16x16x32_bf16 v[30:33], v[152:155], v[212:215], v[30:33]
	v_mfma_f32_16x16x32_bf16 v[26:29], v[168:171], v[212:215], v[26:29]
	v_mfma_f32_16x16x32_bf16 v[14:17], v[152:155], v[220:223], v[14:17]
	v_mfma_f32_16x16x32_bf16 v[10:13], v[168:171], v[220:223], v[10:13]
	s_setprio 0
	s_setprio 1
	v_mfma_f32_16x16x32_bf16 v[54:57], v[172:175], v[188:191], v[54:57]
	v_mfma_f32_16x16x32_bf16 v[50:53], v[180:183], v[188:191], v[50:53]
	v_mfma_f32_16x16x32_bf16 v[38:41], v[172:175], v[200:203], v[38:41]
	v_mfma_f32_16x16x32_bf16 v[34:37], v[180:183], v[200:203], v[34:37]
	v_mfma_f32_16x16x32_bf16 v[22:25], v[172:175], v[208:211], v[22:25]
	v_mfma_f32_16x16x32_bf16 v[18:21], v[180:183], v[208:211], v[18:21]
	v_mfma_f32_16x16x32_bf16 v[6:9], v[172:175], v[216:219], v[6:9]
	v_mfma_f32_16x16x32_bf16 v[2:5], v[180:183], v[216:219], v[2:5]
	v_mfma_f32_16x16x32_bf16 v[54:57], v[176:179], v[192:195], v[54:57]
	v_mfma_f32_16x16x32_bf16 v[50:53], v[184:187], v[192:195], v[50:53]
	v_mfma_f32_16x16x32_bf16 v[38:41], v[176:179], v[204:207], v[38:41]
	v_mfma_f32_16x16x32_bf16 v[34:37], v[184:187], v[204:207], v[34:37]
	v_mfma_f32_16x16x32_bf16 v[22:25], v[176:179], v[212:215], v[22:25]
	v_mfma_f32_16x16x32_bf16 v[18:21], v[184:187], v[212:215], v[18:21]
	v_mfma_f32_16x16x32_bf16 v[6:9], v[176:179], v[220:223], v[6:9]
	v_mfma_f32_16x16x32_bf16 v[2:5], v[184:187], v[220:223], v[2:5]
	s_setprio 0
	s_barrier
	s_add_i32 s85, s85, 2
	s_add_u32 s52, s52, 0x100
	s_addc_u32 s53, s53, 0
	s_add_u32 s83, s83, 0x100
	s_addc_u32 s84, s84, 0
	s_cmp_gt_u32 s85, 13
	s_cbranch_scc0 .LBB0_289
	s_mov_b32 s98, 1
	s_and_b64 vcc, exec, s[18:19]
	s_cbranch_vccz .LBB0_292
	s_barrier

.LBB0_537:
	s_mov_b32 s98, 0
	s_cmp_lt_i32 s34, 5
	s_cselect_b64 s[6:7], -1, 0
	s_and_b64 s[8:9], s[6:7], s[4:5]
	s_andn2_b64 vcc, exec, s[8:9]
	s_cbranch_vccnz .LBB0_580
	s_cmpk_lt_i32 s2, 0x200
	s_cselect_b64 s[4:5], -1, 0
	s_cmpk_gt_i32 s2, 0x1ff
	v_readfirstlane_b32 s20, v0
	s_cbranch_scc1 .LBB0_544
	s_ashr_i32 s6, s2, 31
	s_lshr_b32 s6, s6, 29
	s_add_i32 s10, s2, s6
	s_and_b32 s6, s10, -8
	s_sub_i32 s11, s2, s6
	s_cmp_gt_i32 s11, -1
	s_cbranch_scc0 .LBB0_541
	s_lshl_b32 s12, s11, 6
	s_cbranch_execz .LBB0_542
	s_branch .LBB0_543

.LBB0_557:
	ds_read_b128 v[130:133], v190
	ds_read_b128 v[134:137], v190 offset:1024
	ds_read_b128 v[138:141], v190 offset:2048
	ds_read_b128 v[142:145], v190 offset:3072
	ds_read_b128 v[146:149], v191
	ds_read_b128 v[150:153], v191 offset:1024
	ds_read_b128 v[170:173], v191 offset:2048
	ds_read_b128 v[174:177], v191 offset:3072
	s_add_u32 s54, s52, 0xfffc0080
	s_addc_u32 s55, s53, -1
	s_cmp_eq_u32 s78, 12
	s_cselect_b32 s57, s47, s55
	s_cselect_b32 s56, s74, s54
	s_cselect_b32 s55, s29, s77
	s_cselect_b32 s54, s75, s76
	v_lshl_add_u64 v[186:187], s[52:53], 0, v[162:163]
	s_add_i32 m0, s11, 0xc000
	ds_read_b128 v[178:181], v192
	ds_read_b128 v[182:185], v192 offset:1024
	ds_read_b128 v[194:197], v192 offset:2048
	ds_read_b128 v[200:203], v192 offset:3072
	ds_read_b128 v[204:207], v192 offset:4096
	ds_read_b128 v[208:211], v192 offset:5120
	ds_read_b128 v[212:215], v192 offset:6144
	ds_read_b128 v[216:219], v192 offset:7168
	global_load_lds_dwordx4 v[186:187], off
	v_lshl_add_u64 v[186:187], s[52:53], 0, v[164:165]
	s_add_i32 m0, s11, 0xe000
	s_nop 0
	global_load_lds_dwordx4 v[186:187], off
	s_cmp_eq_u32 s98, 0
	s_cbranch_scc1 .Lrw_strict_p4_0
	s_waitcnt vmcnt(24)
	s_branch .Lrw_done_p4_0

.Lrw_done_p4_0:
	s_waitcnt lgkmcnt(0)
	s_barrier
	s_setprio 1
	s_waitcnt lgkmcnt(0)
	v_mfma_f32_16x16x32_bf16 v[126:129], v[130:133], v[178:181], v[126:129]
	v_mfma_f32_16x16x32_bf16 v[122:125], v[138:141], v[178:181], v[122:125]
	v_mfma_f32_16x16x32_bf16 v[110:113], v[130:133], v[194:197], v[110:113]
	v_mfma_f32_16x16x32_bf16 v[106:109], v[138:141], v[194:197], v[106:109]
	v_mfma_f32_16x16x32_bf16 v[94:97], v[130:133], v[204:207], v[94:97]
	v_mfma_f32_16x16x32_bf16 v[90:93], v[138:141], v[204:207], v[90:93]
	v_mfma_f32_16x16x32_bf16 v[78:81], v[130:133], v[212:215], v[78:81]
	v_mfma_f32_16x16x32_bf16 v[74:77], v[138:141], v[212:215], v[74:77]
	v_mfma_f32_16x16x32_bf16 v[126:129], v[134:137], v[182:185], v[126:129]
	v_mfma_f32_16x16x32_bf16 v[122:125], v[142:145], v[182:185], v[122:125]
	v_mfma_f32_16x16x32_bf16 v[110:113], v[134:137], v[200:203], v[110:113]
	v_mfma_f32_16x16x32_bf16 v[106:109], v[142:145], v[200:203], v[106:109]
	v_mfma_f32_16x16x32_bf16 v[94:97], v[134:137], v[208:211], v[94:97]
	v_mfma_f32_16x16x32_bf16 v[90:93], v[142:145], v[208:211], v[90:93]
	v_mfma_f32_16x16x32_bf16 v[78:81], v[134:137], v[216:219], v[78:81]
	v_mfma_f32_16x16x32_bf16 v[74:77], v[142:145], v[216:219], v[74:77]
	s_setprio 0
	s_setprio 1
	v_mfma_f32_16x16x32_bf16 v[118:121], v[146:149], v[178:181], v[118:121]
	v_mfma_f32_16x16x32_bf16 v[114:117], v[170:173], v[178:181], v[114:117]
	v_mfma_f32_16x16x32_bf16 v[102:105], v[146:149], v[194:197], v[102:105]
	v_mfma_f32_16x16x32_bf16 v[98:101], v[170:173], v[194:197], v[98:101]
	v_mfma_f32_16x16x32_bf16 v[86:89], v[146:149], v[204:207], v[86:89]
	v_mfma_f32_16x16x32_bf16 v[82:85], v[170:173], v[204:207], v[82:85]
	v_mfma_f32_16x16x32_bf16 v[70:73], v[146:149], v[212:215], v[70:73]
	v_mfma_f32_16x16x32_bf16 v[66:69], v[170:173], v[212:215], v[66:69]
	v_mfma_f32_16x16x32_bf16 v[118:121], v[150:153], v[182:185], v[118:121]
	v_mfma_f32_16x16x32_bf16 v[114:117], v[174:177], v[182:185], v[114:117]
	v_mfma_f32_16x16x32_bf16 v[102:105], v[150:153], v[200:203], v[102:105]
	v_mfma_f32_16x16x32_bf16 v[98:101], v[174:177], v[200:203], v[98:101]
	v_mfma_f32_16x16x32_bf16 v[86:89], v[150:153], v[208:211], v[86:89]
	v_mfma_f32_16x16x32_bf16 v[82:85], v[174:177], v[208:211], v[82:85]
	v_mfma_f32_16x16x32_bf16 v[70:73], v[150:153], v[216:219], v[70:73]
	v_mfma_f32_16x16x32_bf16 v[66:69], v[174:177], v[216:219], v[66:69]
	s_setprio 0
	s_barrier
	s_add_i32 s79, s71, s62
	v_lshl_add_u64 v[186:187], s[54:55], 0, v[156:157]
	s_mov_b32 m0, s79
	ds_read_b128 v[178:181], v192 offset:16384
	ds_read_b128 v[182:185], v192 offset:17408
	ds_read_b128 v[194:197], v192 offset:18432
	ds_read_b128 v[200:203], v192 offset:19456
	ds_read_b128 v[204:207], v192 offset:20480
	ds_read_b128 v[208:211], v192 offset:21504
	ds_read_b128 v[212:215], v192 offset:22528
	ds_read_b128 v[216:219], v192 offset:23552
	global_load_lds_dwordx4 v[186:187], off
	s_add_i32 m0, s79, 0x2000
	s_add_u32 s80, s54, 0x40000
	v_lshl_add_u64 v[220:221], s[54:55], 0, v[160:161]
	s_addc_u32 s81, s55, 0
	s_add_i32 s79, s72, s62
	global_load_lds_dwordx4 v[220:221], off
	v_lshl_add_u64 v[222:223], s[80:81], 0, v[156:157]
	s_mov_b32 m0, s79
	v_lshl_add_u64 v[224:225], s[56:57], 0, v[158:159]
	global_load_lds_dwordx4 v[222:223], off
	v_lshl_add_u64 v[222:223], s[80:81], 0, v[160:161]
	s_add_i32 m0, s79, 0x2000
	s_nop 0
	global_load_lds_dwordx4 v[222:223], off
	v_lshl_add_u64 v[222:223], s[56:57], 0, v[154:155]
	s_mov_b32 m0, s11
	s_nop 0
	global_load_lds_dwordx4 v[222:223], off
	s_mov_b32 m0, s63
	s_nop 0
	global_load_lds_dwordx4 v[224:225], off
	s_cmp_eq_u32 s98, 0
	s_cbranch_scc1 .Lrw_strict_p4_1
	s_waitcnt vmcnt(24)
	s_branch .Lrw_done_p4_1

.Lrw_done_p4_1:
	s_mov_b32 s98, 0
	s_waitcnt lgkmcnt(0)
	s_barrier
	s_setprio 1
	s_waitcnt lgkmcnt(0)
	v_mfma_f32_16x16x32_bf16 v[62:65], v[130:133], v[178:181], v[62:65]
	v_mfma_f32_16x16x32_bf16 v[58:61], v[138:141], v[178:181], v[58:61]
	v_mfma_f32_16x16x32_bf16 v[46:49], v[130:133], v[194:197], v[46:49]
	v_mfma_f32_16x16x32_bf16 v[42:45], v[138:141], v[194:197], v[42:45]
	v_mfma_f32_16x16x32_bf16 v[30:33], v[130:133], v[204:207], v[30:33]
	v_mfma_f32_16x16x32_bf16 v[26:29], v[138:141], v[204:207], v[26:29]
	v_mfma_f32_16x16x32_bf16 v[14:17], v[130:133], v[212:215], v[14:17]
	v_mfma_f32_16x16x32_bf16 v[10:13], v[138:141], v[212:215], v[10:13]
	v_mfma_f32_16x16x32_bf16 v[62:65], v[134:137], v[182:185], v[62:65]
	v_mfma_f32_16x16x32_bf16 v[58:61], v[142:145], v[182:185], v[58:61]
	v_mfma_f32_16x16x32_bf16 v[46:49], v[134:137], v[200:203], v[46:49]
	v_mfma_f32_16x16x32_bf16 v[42:45], v[142:145], v[200:203], v[42:45]
	v_mfma_f32_16x16x32_bf16 v[30:33], v[134:137], v[208:211], v[30:33]
	v_mfma_f32_16x16x32_bf16 v[26:29], v[142:145], v[208:211], v[26:29]
	v_mfma_f32_16x16x32_bf16 v[14:17], v[134:137], v[216:219], v[14:17]
	v_mfma_f32_16x16x32_bf16 v[10:13], v[142:145], v[216:219], v[10:13]
	s_setprio 0
	s_setprio 1
	v_mfma_f32_16x16x32_bf16 v[54:57], v[146:149], v[178:181], v[54:57]
	v_mfma_f32_16x16x32_bf16 v[50:53], v[170:173], v[178:181], v[50:53]
	v_mfma_f32_16x16x32_bf16 v[38:41], v[146:149], v[194:197], v[38:41]
	v_mfma_f32_16x16x32_bf16 v[34:37], v[170:173], v[194:197], v[34:37]
	v_mfma_f32_16x16x32_bf16 v[22:25], v[146:149], v[204:207], v[22:25]
	v_mfma_f32_16x16x32_bf16 v[18:21], v[170:173], v[204:207], v[18:21]
	v_mfma_f32_16x16x32_bf16 v[6:9], v[146:149], v[212:215], v[6:9]
	v_mfma_f32_16x16x32_bf16 v[2:5], v[170:173], v[212:215], v[2:5]
	v_mfma_f32_16x16x32_bf16 v[54:57], v[150:153], v[182:185], v[54:57]
	v_mfma_f32_16x16x32_bf16 v[50:53], v[174:177], v[182:185], v[50:53]
	v_mfma_f32_16x16x32_bf16 v[38:41], v[150:153], v[200:203], v[38:41]
	v_mfma_f32_16x16x32_bf16 v[34:37], v[174:177], v[200:203], v[34:37]
	v_mfma_f32_16x16x32_bf16 v[22:25], v[150:153], v[208:211], v[22:25]
	v_mfma_f32_16x16x32_bf16 v[18:21], v[174:177], v[208:211], v[18:21]
	v_mfma_f32_16x16x32_bf16 v[6:9], v[150:153], v[216:219], v[6:9]
	v_mfma_f32_16x16x32_bf16 v[2:5], v[174:177], v[216:219], v[2:5]
	s_setprio 0
	s_barrier
	s_add_i32 s79, 0, 0x18000
	s_add_i32 s80, 0, 0x1c000
	v_add_u32_e32 v142, s79, v188
	v_add_u32_e32 v174, s80, v188
	ds_read_b128 v[130:133], v142
	ds_read_b128 v[134:137], v142 offset:1024
	ds_read_b128 v[138:141], v142 offset:2048
	ds_read_b128 v[142:145], v142 offset:3072
	ds_read_b128 v[146:149], v174
	ds_read_b128 v[150:153], v174 offset:1024
	ds_read_b128 v[170:173], v174 offset:2048
	ds_read_b128 v[174:177], v174 offset:3072
	s_add_u32 s56, s56, 0x40000
	s_addc_u32 s57, s57, 0
	s_mov_b32 m0, s64
	v_lshl_add_u64 v[226:227], s[56:57], 0, v[154:155]
	ds_read_b128 v[178:181], v192 offset:32768
	ds_read_b128 v[182:185], v192 offset:33792
	ds_read_b128 v[194:197], v192 offset:34816
	ds_read_b128 v[200:203], v192 offset:35840
	ds_read_b128 v[204:207], v192 offset:36864
	ds_read_b128 v[208:211], v192 offset:37888
	ds_read_b128 v[212:215], v192 offset:38912
	ds_read_b128 v[216:219], v192 offset:39936
	global_load_lds_dwordx4 v[226:227], off
	v_lshl_add_u64 v[226:227], s[56:57], 0, v[158:159]
	s_mov_b32 m0, s65
	s_nop 0
	global_load_lds_dwordx4 v[226:227], off
	s_waitcnt vmcnt(8)
	s_waitcnt lgkmcnt(0)
	s_barrier
	s_setprio 1
	s_waitcnt lgkmcnt(0)
	v_mfma_f32_16x16x32_bf16 v[126:129], v[130:133], v[178:181], v[126:129]
	v_mfma_f32_16x16x32_bf16 v[122:125], v[138:141], v[178:181], v[122:125]
	v_mfma_f32_16x16x32_bf16 v[110:113], v[130:133], v[194:197], v[110:113]
	v_mfma_f32_16x16x32_bf16 v[106:109], v[138:141], v[194:197], v[106:109]
	v_mfma_f32_16x16x32_bf16 v[94:97], v[130:133], v[204:207], v[94:97]
	v_mfma_f32_16x16x32_bf16 v[90:93], v[138:141], v[204:207], v[90:93]
	v_mfma_f32_16x16x32_bf16 v[78:81], v[130:133], v[212:215], v[78:81]
	v_mfma_f32_16x16x32_bf16 v[74:77], v[138:141], v[212:215], v[74:77]
	v_mfma_f32_16x16x32_bf16 v[126:129], v[134:137], v[182:185], v[126:129]
	v_mfma_f32_16x16x32_bf16 v[122:125], v[142:145], v[182:185], v[122:125]
	v_mfma_f32_16x16x32_bf16 v[110:113], v[134:137], v[200:203], v[110:113]
	v_mfma_f32_16x16x32_bf16 v[106:109], v[142:145], v[200:203], v[106:109]
	v_mfma_f32_16x16x32_bf16 v[94:97], v[134:137], v[208:211], v[94:97]
	v_mfma_f32_16x16x32_bf16 v[90:93], v[142:145], v[208:211], v[90:93]
	v_mfma_f32_16x16x32_bf16 v[78:81], v[134:137], v[216:219], v[78:81]
	v_mfma_f32_16x16x32_bf16 v[74:77], v[142:145], v[216:219], v[74:77]
	s_setprio 0
	s_setprio 1
	v_mfma_f32_16x16x32_bf16 v[118:121], v[146:149], v[178:181], v[118:121]
	v_mfma_f32_16x16x32_bf16 v[114:117], v[170:173], v[178:181], v[114:117]
	v_mfma_f32_16x16x32_bf16 v[102:105], v[146:149], v[194:197], v[102:105]
	v_mfma_f32_16x16x32_bf16 v[98:101], v[170:173], v[194:197], v[98:101]
	v_mfma_f32_16x16x32_bf16 v[86:89], v[146:149], v[204:207], v[86:89]
	v_mfma_f32_16x16x32_bf16 v[82:85], v[170:173], v[204:207], v[82:85]
	v_mfma_f32_16x16x32_bf16 v[70:73], v[146:149], v[212:215], v[70:73]
	v_mfma_f32_16x16x32_bf16 v[66:69], v[170:173], v[212:215], v[66:69]
	v_mfma_f32_16x16x32_bf16 v[118:121], v[150:153], v[182:185], v[118:121]
	v_mfma_f32_16x16x32_bf16 v[114:117], v[174:177], v[182:185], v[114:117]
	v_mfma_f32_16x16x32_bf16 v[102:105], v[150:153], v[200:203], v[102:105]
	v_mfma_f32_16x16x32_bf16 v[98:101], v[174:177], v[200:203], v[98:101]
	v_mfma_f32_16x16x32_bf16 v[86:89], v[150:153], v[208:211], v[86:89]
	v_mfma_f32_16x16x32_bf16 v[82:85], v[174:177], v[208:211], v[82:85]
	v_mfma_f32_16x16x32_bf16 v[70:73], v[150:153], v[216:219], v[70:73]
	v_mfma_f32_16x16x32_bf16 v[66:69], v[174:177], v[216:219], v[66:69]
	s_setprio 0
	s_barrier
	s_add_i32 s56, s79, s62
	v_lshl_add_u64 v[186:187], v[186:187], 0, s[18:19]
	s_mov_b32 m0, s56
	ds_read_b128 v[178:181], v192 offset:49152
	ds_read_b128 v[182:185], v192 offset:50176
	ds_read_b128 v[194:197], v192 offset:51200
	ds_read_b128 v[200:203], v192 offset:52224
	ds_read_b128 v[204:207], v192 offset:53248
	ds_read_b128 v[208:211], v192 offset:54272
	ds_read_b128 v[212:215], v192 offset:55296
	ds_read_b128 v[216:219], v192 offset:56320
	global_load_lds_dwordx4 v[186:187], off
	s_add_i32 m0, s56, 0x2000
	s_add_u32 s54, s54, 0x40080
	v_lshl_add_u64 v[186:187], v[220:221], 0, s[18:19]
	s_addc_u32 s55, s55, 0
	s_add_i32 s56, s80, s62
	global_load_lds_dwordx4 v[186:187], off
	v_lshl_add_u64 v[186:187], s[54:55], 0, v[156:157]
	s_mov_b32 m0, s56
	s_nop 0
	global_load_lds_dwordx4 v[186:187], off
	v_lshl_add_u64 v[186:187], s[54:55], 0, v[160:161]
	s_add_i32 m0, s56, 0x2000
	s_nop 0
	global_load_lds_dwordx4 v[186:187], off
	v_lshl_add_u64 v[186:187], v[222:223], 0, s[18:19]
	s_mov_b32 m0, s67
	s_nop 0
	global_load_lds_dwordx4 v[186:187], off
	v_lshl_add_u64 v[186:187], v[224:225], 0, s[18:19]
	s_mov_b32 m0, s68
	s_nop 0
	global_load_lds_dwordx4 v[186:187], off
	s_waitcnt vmcnt(8)
	s_waitcnt lgkmcnt(0)
	s_barrier
	s_setprio 1
	s_waitcnt lgkmcnt(0)
	v_mfma_f32_16x16x32_bf16 v[62:65], v[130:133], v[178:181], v[62:65]
	v_mfma_f32_16x16x32_bf16 v[58:61], v[138:141], v[178:181], v[58:61]
	v_mfma_f32_16x16x32_bf16 v[46:49], v[130:133], v[194:197], v[46:49]
	v_mfma_f32_16x16x32_bf16 v[42:45], v[138:141], v[194:197], v[42:45]
	v_mfma_f32_16x16x32_bf16 v[30:33], v[130:133], v[204:207], v[30:33]
	v_mfma_f32_16x16x32_bf16 v[26:29], v[138:141], v[204:207], v[26:29]
	v_mfma_f32_16x16x32_bf16 v[14:17], v[130:133], v[212:215], v[14:17]
	v_mfma_f32_16x16x32_bf16 v[10:13], v[138:141], v[212:215], v[10:13]
	v_mfma_f32_16x16x32_bf16 v[62:65], v[134:137], v[182:185], v[62:65]
	v_mfma_f32_16x16x32_bf16 v[58:61], v[142:145], v[182:185], v[58:61]
	v_mfma_f32_16x16x32_bf16 v[46:49], v[134:137], v[200:203], v[46:49]
	v_mfma_f32_16x16x32_bf16 v[42:45], v[142:145], v[200:203], v[42:45]
	v_mfma_f32_16x16x32_bf16 v[30:33], v[134:137], v[208:211], v[30:33]
	v_mfma_f32_16x16x32_bf16 v[26:29], v[142:145], v[208:211], v[26:29]
	v_mfma_f32_16x16x32_bf16 v[14:17], v[134:137], v[216:219], v[14:17]
	v_mfma_f32_16x16x32_bf16 v[10:13], v[142:145], v[216:219], v[10:13]
	s_setprio 0
	s_setprio 1
	v_mfma_f32_16x16x32_bf16 v[54:57], v[146:149], v[178:181], v[54:57]
	v_mfma_f32_16x16x32_bf16 v[50:53], v[170:173], v[178:181], v[50:53]
	v_mfma_f32_16x16x32_bf16 v[38:41], v[146:149], v[194:197], v[38:41]
	v_mfma_f32_16x16x32_bf16 v[34:37], v[170:173], v[194:197], v[34:37]
	v_mfma_f32_16x16x32_bf16 v[22:25], v[146:149], v[204:207], v[22:25]
	v_mfma_f32_16x16x32_bf16 v[18:21], v[170:173], v[204:207], v[18:21]
	v_mfma_f32_16x16x32_bf16 v[6:9], v[146:149], v[212:215], v[6:9]
	v_mfma_f32_16x16x32_bf16 v[2:5], v[170:173], v[212:215], v[2:5]
	v_mfma_f32_16x16x32_bf16 v[54:57], v[150:153], v[182:185], v[54:57]
	v_mfma_f32_16x16x32_bf16 v[50:53], v[174:177], v[182:185], v[50:53]
	v_mfma_f32_16x16x32_bf16 v[38:41], v[150:153], v[200:203], v[38:41]
	v_mfma_f32_16x16x32_bf16 v[34:37], v[174:177], v[200:203], v[34:37]
	v_mfma_f32_16x16x32_bf16 v[22:25], v[150:153], v[208:211], v[22:25]
	v_mfma_f32_16x16x32_bf16 v[18:21], v[174:177], v[208:211], v[18:21]
	v_mfma_f32_16x16x32_bf16 v[6:9], v[150:153], v[216:219], v[6:9]
	v_mfma_f32_16x16x32_bf16 v[2:5], v[174:177], v[216:219], v[2:5]
	s_setprio 0
	s_barrier
	s_add_i32 s78, s78, 2
	s_add_u32 s52, s52, 0x100
	s_addc_u32 s53, s53, 0
	s_add_u32 s76, s76, 0x100
	s_addc_u32 s77, s77, 0
	s_cmp_gt_u32 s78, 13
	s_cbranch_scc0 .LBB0_557
	s_mov_b32 s98, 1
	s_and_b64 vcc, exec, s[20:21]
	s_cbranch_vccz .LBB0_560
	s_barrier

.LBB0_629:
	s_mov_b32 s98, 0
	s_cmp_lt_i32 s34, 6
	s_cselect_b64 s[6:7], -1, 0
	s_and_b64 s[14:15], s[6:7], s[4:5]
	s_andn2_b64 vcc, exec, s[14:15]
	s_cbranch_vccnz .LBB0_798
	s_add_i32 s6, 0, 0x22800
	s_add_u32 s10, s38, 0x1400000
	s_addc_u32 s11, s39, 0
	s_cmpk_lt_i32 s2, 0x800
	s_movk_i32 s4, 0x100
	s_cselect_b64 s[8:9], -1, 0
	v_cmp_gt_u32_e64 s[4:5], s4, v0
	v_lshl_add_u32 v1, v0, 2, s6
	s_and_b64 vcc, exec, s[8:9]
	s_cbranch_vccz .LBB0_638
	s_ashr_i32 s6, s2, 31
	s_lshr_b32 s6, s6, 29
	s_add_i32 s18, s2, s6
	s_and_b32 s6, s18, -8
	s_sub_i32 s12, s2, s6
	s_cmp_gt_i32 s12, -1
	s_cbranch_scc0 .LBB0_633
	s_lshl_b32 s19, s12, 8
	s_cbranch_execz .LBB0_634
	s_branch .LBB0_635

.LBB0_713:
	ds_read_b128 v[130:133], v243
	ds_read_b128 v[134:137], v243 offset:1024
	ds_read_b128 v[138:141], v243 offset:2048
	ds_read_b128 v[142:145], v243 offset:3072
	ds_read_b128 v[146:149], v244
	ds_read_b128 v[150:153], v244 offset:1024
	ds_read_b128 v[154:157], v244 offset:2048
	ds_read_b128 v[158:161], v244 offset:3072
	s_add_u32 s62, s12, 0xfffc0080
	s_addc_u32 s63, s13, -1
	s_cmp_eq_u32 s95, 12
	s_cselect_b32 s65, s57, s63
	s_cselect_b32 s64, s67, s62
	s_cselect_b32 s63, s55, s94
	s_cselect_b32 s62, s92, s93
	v_lshl_add_u64 v[194:195], s[12:13], 0, v[216:217]
	s_add_i32 m0, s25, 0xc000
	ds_read_b128 v[162:165], v245
	ds_read_b128 v[166:169], v245 offset:1024
	ds_read_b128 v[170:173], v245 offset:2048
	ds_read_b128 v[174:177], v245 offset:3072
	ds_read_b128 v[178:181], v245 offset:4096
	ds_read_b128 v[182:185], v245 offset:5120
	ds_read_b128 v[186:189], v245 offset:6144
	ds_read_b128 v[190:193], v245 offset:7168
	global_load_lds_dwordx4 v[194:195], off
	v_lshl_add_u64 v[194:195], s[12:13], 0, v[218:219]
	s_add_i32 m0, s25, 0xe000
	s_nop 0
	global_load_lds_dwordx4 v[194:195], off
	s_cmp_eq_u32 s98, 0
	s_cbranch_scc1 .Lrw_strict_p5_0
	s_waitcnt vmcnt(24)
	s_branch .Lrw_done_p5_0

.Lrw_done_p5_0:
	s_waitcnt lgkmcnt(0)
	s_barrier
	s_setprio 1
	s_waitcnt lgkmcnt(0)
	v_mfma_f32_16x16x32_bf16 v[126:129], v[130:133], v[162:165], v[126:129]
	v_mfma_f32_16x16x32_bf16 v[122:125], v[138:141], v[162:165], v[122:125]
	v_mfma_f32_16x16x32_bf16 v[110:113], v[130:133], v[170:173], v[110:113]
	v_mfma_f32_16x16x32_bf16 v[106:109], v[138:141], v[170:173], v[106:109]
	v_mfma_f32_16x16x32_bf16 v[94:97], v[130:133], v[178:181], v[94:97]
	v_mfma_f32_16x16x32_bf16 v[90:93], v[138:141], v[178:181], v[90:93]
	v_mfma_f32_16x16x32_bf16 v[78:81], v[130:133], v[186:189], v[78:81]
	v_mfma_f32_16x16x32_bf16 v[74:77], v[138:141], v[186:189], v[74:77]
	v_mfma_f32_16x16x32_bf16 v[126:129], v[134:137], v[166:169], v[126:129]
	v_mfma_f32_16x16x32_bf16 v[122:125], v[142:145], v[166:169], v[122:125]
	v_mfma_f32_16x16x32_bf16 v[110:113], v[134:137], v[174:177], v[110:113]
	v_mfma_f32_16x16x32_bf16 v[106:109], v[142:145], v[174:177], v[106:109]
	v_mfma_f32_16x16x32_bf16 v[94:97], v[134:137], v[182:185], v[94:97]
	v_mfma_f32_16x16x32_bf16 v[90:93], v[142:145], v[182:185], v[90:93]
	v_mfma_f32_16x16x32_bf16 v[78:81], v[134:137], v[190:193], v[78:81]
	v_mfma_f32_16x16x32_bf16 v[74:77], v[142:145], v[190:193], v[74:77]
	s_setprio 0
	s_setprio 1
	v_mfma_f32_16x16x32_bf16 v[118:121], v[146:149], v[162:165], v[118:121]
	v_mfma_f32_16x16x32_bf16 v[114:117], v[154:157], v[162:165], v[114:117]
	v_mfma_f32_16x16x32_bf16 v[102:105], v[146:149], v[170:173], v[102:105]
	v_mfma_f32_16x16x32_bf16 v[98:101], v[154:157], v[170:173], v[98:101]
	v_mfma_f32_16x16x32_bf16 v[86:89], v[146:149], v[178:181], v[86:89]
	v_mfma_f32_16x16x32_bf16 v[82:85], v[154:157], v[178:181], v[82:85]
	v_mfma_f32_16x16x32_bf16 v[70:73], v[146:149], v[186:189], v[70:73]
	v_mfma_f32_16x16x32_bf16 v[66:69], v[154:157], v[186:189], v[66:69]
	v_mfma_f32_16x16x32_bf16 v[118:121], v[150:153], v[166:169], v[118:121]
	v_mfma_f32_16x16x32_bf16 v[114:117], v[158:161], v[166:169], v[114:117]
	v_mfma_f32_16x16x32_bf16 v[102:105], v[150:153], v[174:177], v[102:105]
	v_mfma_f32_16x16x32_bf16 v[98:101], v[158:161], v[174:177], v[98:101]
	v_mfma_f32_16x16x32_bf16 v[86:89], v[150:153], v[182:185], v[86:89]
	v_mfma_f32_16x16x32_bf16 v[82:85], v[158:161], v[182:185], v[82:85]
	v_mfma_f32_16x16x32_bf16 v[70:73], v[150:153], v[190:193], v[70:73]
	v_mfma_f32_16x16x32_bf16 v[66:69], v[158:161], v[190:193], v[66:69]
	s_setprio 0
	s_barrier
	s_add_i32 s96, s85, s73
	v_lshl_add_u64 v[194:195], s[62:63], 0, v[202:203]
	s_mov_b32 m0, s96
	ds_read_b128 v[162:165], v245 offset:16384
	ds_read_b128 v[166:169], v245 offset:17408
	ds_read_b128 v[170:173], v245 offset:18432
	ds_read_b128 v[174:177], v245 offset:19456
	ds_read_b128 v[178:181], v245 offset:20480
	ds_read_b128 v[182:185], v245 offset:21504
	ds_read_b128 v[186:189], v245 offset:22528
	ds_read_b128 v[190:193], v245 offset:23552
	global_load_lds_dwordx4 v[194:195], off
	s_add_i32 m0, s96, 0x2000
	s_add_u32 s96, s62, 0x40000
	v_lshl_add_u64 v[196:197], s[62:63], 0, v[206:207]
	s_addc_u32 s97, s63, 0
	s_add_i32 vcc_lo, s86, s73
	global_load_lds_dwordx4 v[196:197], off
	v_lshl_add_u64 v[220:221], s[96:97], 0, v[202:203]
	s_mov_b32 m0, vcc_lo
	v_lshl_add_u64 v[222:223], s[64:65], 0, v[204:205]
	global_load_lds_dwordx4 v[220:221], off
	v_lshl_add_u64 v[220:221], s[96:97], 0, v[206:207]
	s_add_i32 m0, vcc_lo, 0x2000
	s_nop 0
	global_load_lds_dwordx4 v[220:221], off
	v_lshl_add_u64 v[220:221], s[64:65], 0, v[200:201]
	s_mov_b32 m0, s25
	s_nop 0
	global_load_lds_dwordx4 v[220:221], off
	s_mov_b32 m0, s74
	s_nop 0
	global_load_lds_dwordx4 v[222:223], off
	s_cmp_eq_u32 s98, 0
	s_cbranch_scc1 .Lrw_strict_p5_1
	s_waitcnt vmcnt(24)
	s_branch .Lrw_done_p5_1

.Lrw_done_p5_1:
	s_mov_b32 s98, 0
	s_waitcnt lgkmcnt(0)
	s_barrier
	s_setprio 1
	s_waitcnt lgkmcnt(0)
	v_mfma_f32_16x16x32_bf16 v[62:65], v[130:133], v[162:165], v[62:65]
	v_mfma_f32_16x16x32_bf16 v[58:61], v[138:141], v[162:165], v[58:61]
	v_mfma_f32_16x16x32_bf16 v[46:49], v[130:133], v[170:173], v[46:49]
	v_mfma_f32_16x16x32_bf16 v[42:45], v[138:141], v[170:173], v[42:45]
	v_mfma_f32_16x16x32_bf16 v[30:33], v[130:133], v[178:181], v[30:33]
	v_mfma_f32_16x16x32_bf16 v[26:29], v[138:141], v[178:181], v[26:29]
	v_mfma_f32_16x16x32_bf16 v[14:17], v[130:133], v[186:189], v[14:17]
	v_mfma_f32_16x16x32_bf16 v[10:13], v[138:141], v[186:189], v[10:13]
	v_mfma_f32_16x16x32_bf16 v[62:65], v[134:137], v[166:169], v[62:65]
	v_mfma_f32_16x16x32_bf16 v[58:61], v[142:145], v[166:169], v[58:61]
	v_mfma_f32_16x16x32_bf16 v[46:49], v[134:137], v[174:177], v[46:49]
	v_mfma_f32_16x16x32_bf16 v[42:45], v[142:145], v[174:177], v[42:45]
	v_mfma_f32_16x16x32_bf16 v[30:33], v[134:137], v[182:185], v[30:33]
	v_mfma_f32_16x16x32_bf16 v[26:29], v[142:145], v[182:185], v[26:29]
	v_mfma_f32_16x16x32_bf16 v[14:17], v[134:137], v[190:193], v[14:17]
	v_mfma_f32_16x16x32_bf16 v[10:13], v[142:145], v[190:193], v[10:13]
	s_setprio 0
	s_setprio 1
	v_mfma_f32_16x16x32_bf16 v[54:57], v[146:149], v[162:165], v[54:57]
	v_mfma_f32_16x16x32_bf16 v[50:53], v[154:157], v[162:165], v[50:53]
	v_mfma_f32_16x16x32_bf16 v[38:41], v[146:149], v[170:173], v[38:41]
	v_mfma_f32_16x16x32_bf16 v[34:37], v[154:157], v[170:173], v[34:37]
	v_mfma_f32_16x16x32_bf16 v[22:25], v[146:149], v[178:181], v[22:25]
	v_mfma_f32_16x16x32_bf16 v[18:21], v[154:157], v[178:181], v[18:21]
	v_mfma_f32_16x16x32_bf16 v[6:9], v[146:149], v[186:189], v[6:9]
	v_mfma_f32_16x16x32_bf16 v[2:5], v[154:157], v[186:189], v[2:5]
	v_mfma_f32_16x16x32_bf16 v[54:57], v[150:153], v[166:169], v[54:57]
	v_mfma_f32_16x16x32_bf16 v[50:53], v[158:161], v[166:169], v[50:53]
	v_mfma_f32_16x16x32_bf16 v[38:41], v[150:153], v[174:177], v[38:41]
	v_mfma_f32_16x16x32_bf16 v[34:37], v[158:161], v[174:177], v[34:37]
	v_mfma_f32_16x16x32_bf16 v[22:25], v[150:153], v[182:185], v[22:25]
	v_mfma_f32_16x16x32_bf16 v[18:21], v[158:161], v[182:185], v[18:21]
	v_mfma_f32_16x16x32_bf16 v[6:9], v[150:153], v[190:193], v[6:9]
	v_mfma_f32_16x16x32_bf16 v[2:5], v[158:161], v[190:193], v[2:5]
	s_setprio 0
	s_barrier
	s_add_i32 s96, 0, 0x18000
	s_add_i32 s97, 0, 0x1c000
	v_add_u32_e32 v142, s96, v199
	v_add_u32_e32 v158, s97, v199
	ds_read_b128 v[130:133], v142
	ds_read_b128 v[134:137], v142 offset:1024
	ds_read_b128 v[138:141], v142 offset:2048
	ds_read_b128 v[142:145], v142 offset:3072
	ds_read_b128 v[146:149], v158
	ds_read_b128 v[150:153], v158 offset:1024
	ds_read_b128 v[154:157], v158 offset:2048
	ds_read_b128 v[158:161], v158 offset:3072
	s_add_u32 s64, s64, 0x40000
	s_addc_u32 s65, s65, 0
	s_mov_b32 m0, s75
	v_lshl_add_u64 v[224:225], s[64:65], 0, v[200:201]
	ds_read_b128 v[162:165], v245 offset:32768
	ds_read_b128 v[166:169], v245 offset:33792
	ds_read_b128 v[170:173], v245 offset:34816
	ds_read_b128 v[174:177], v245 offset:35840
	ds_read_b128 v[178:181], v245 offset:36864
	ds_read_b128 v[182:185], v245 offset:37888
	ds_read_b128 v[186:189], v245 offset:38912
	ds_read_b128 v[190:193], v245 offset:39936
	global_load_lds_dwordx4 v[224:225], off
	v_lshl_add_u64 v[224:225], s[64:65], 0, v[204:205]
	s_mov_b32 m0, s76
	s_nop 0
	global_load_lds_dwordx4 v[224:225], off
	s_waitcnt vmcnt(8)
	s_waitcnt lgkmcnt(0)
	s_barrier
	s_setprio 1
	s_waitcnt lgkmcnt(0)
	v_mfma_f32_16x16x32_bf16 v[126:129], v[130:133], v[162:165], v[126:129]
	v_mfma_f32_16x16x32_bf16 v[122:125], v[138:141], v[162:165], v[122:125]
	v_mfma_f32_16x16x32_bf16 v[110:113], v[130:133], v[170:173], v[110:113]
	v_mfma_f32_16x16x32_bf16 v[106:109], v[138:141], v[170:173], v[106:109]
	v_mfma_f32_16x16x32_bf16 v[94:97], v[130:133], v[178:181], v[94:97]
	v_mfma_f32_16x16x32_bf16 v[90:93], v[138:141], v[178:181], v[90:93]
	v_mfma_f32_16x16x32_bf16 v[78:81], v[130:133], v[186:189], v[78:81]
	v_mfma_f32_16x16x32_bf16 v[74:77], v[138:141], v[186:189], v[74:77]
	v_mfma_f32_16x16x32_bf16 v[126:129], v[134:137], v[166:169], v[126:129]
	v_mfma_f32_16x16x32_bf16 v[122:125], v[142:145], v[166:169], v[122:125]
	v_mfma_f32_16x16x32_bf16 v[110:113], v[134:137], v[174:177], v[110:113]
	v_mfma_f32_16x16x32_bf16 v[106:109], v[142:145], v[174:177], v[106:109]
	v_mfma_f32_16x16x32_bf16 v[94:97], v[134:137], v[182:185], v[94:97]
	v_mfma_f32_16x16x32_bf16 v[90:93], v[142:145], v[182:185], v[90:93]
	v_mfma_f32_16x16x32_bf16 v[78:81], v[134:137], v[190:193], v[78:81]
	v_mfma_f32_16x16x32_bf16 v[74:77], v[142:145], v[190:193], v[74:77]
	s_setprio 0
	s_setprio 1
	v_mfma_f32_16x16x32_bf16 v[118:121], v[146:149], v[162:165], v[118:121]
	v_mfma_f32_16x16x32_bf16 v[114:117], v[154:157], v[162:165], v[114:117]
	v_mfma_f32_16x16x32_bf16 v[102:105], v[146:149], v[170:173], v[102:105]
	v_mfma_f32_16x16x32_bf16 v[98:101], v[154:157], v[170:173], v[98:101]
	v_mfma_f32_16x16x32_bf16 v[86:89], v[146:149], v[178:181], v[86:89]
	v_mfma_f32_16x16x32_bf16 v[82:85], v[154:157], v[178:181], v[82:85]
	v_mfma_f32_16x16x32_bf16 v[70:73], v[146:149], v[186:189], v[70:73]
	v_mfma_f32_16x16x32_bf16 v[66:69], v[154:157], v[186:189], v[66:69]
	v_mfma_f32_16x16x32_bf16 v[118:121], v[150:153], v[166:169], v[118:121]
	v_mfma_f32_16x16x32_bf16 v[114:117], v[158:161], v[166:169], v[114:117]
	v_mfma_f32_16x16x32_bf16 v[102:105], v[150:153], v[174:177], v[102:105]
	v_mfma_f32_16x16x32_bf16 v[98:101], v[158:161], v[174:177], v[98:101]
	v_mfma_f32_16x16x32_bf16 v[86:89], v[150:153], v[182:185], v[86:89]
	v_mfma_f32_16x16x32_bf16 v[82:85], v[158:161], v[182:185], v[82:85]
	v_mfma_f32_16x16x32_bf16 v[70:73], v[150:153], v[190:193], v[70:73]
	v_mfma_f32_16x16x32_bf16 v[66:69], v[158:161], v[190:193], v[66:69]
	s_setprio 0
	s_barrier
	s_add_i32 s64, s96, s73
	v_lshl_add_u64 v[194:195], v[194:195], 0, s[26:27]
	s_mov_b32 m0, s64
	ds_read_b128 v[162:165], v245 offset:49152
	ds_read_b128 v[166:169], v245 offset:50176
	ds_read_b128 v[170:173], v245 offset:51200
	ds_read_b128 v[174:177], v245 offset:52224
	ds_read_b128 v[178:181], v245 offset:53248
	ds_read_b128 v[182:185], v245 offset:54272
	ds_read_b128 v[186:189], v245 offset:55296
	ds_read_b128 v[190:193], v245 offset:56320
	global_load_lds_dwordx4 v[194:195], off
	s_add_i32 m0, s64, 0x2000
	s_add_u32 s62, s62, 0x40080
	v_lshl_add_u64 v[194:195], v[196:197], 0, s[26:27]
	s_addc_u32 s63, s63, 0
	s_add_i32 s64, s97, s73
	global_load_lds_dwordx4 v[194:195], off
	v_lshl_add_u64 v[194:195], s[62:63], 0, v[202:203]
	s_mov_b32 m0, s64
	s_nop 0
	global_load_lds_dwordx4 v[194:195], off
	v_lshl_add_u64 v[194:195], s[62:63], 0, v[206:207]
	s_add_i32 m0, s64, 0x2000
	s_nop 0
	global_load_lds_dwordx4 v[194:195], off
	v_lshl_add_u64 v[194:195], v[220:221], 0, s[26:27]
	s_mov_b32 m0, s77
	s_nop 0
	global_load_lds_dwordx4 v[194:195], off
	v_lshl_add_u64 v[194:195], v[222:223], 0, s[26:27]
	s_mov_b32 m0, s78
	s_nop 0
	global_load_lds_dwordx4 v[194:195], off
	s_waitcnt vmcnt(8)
	s_waitcnt lgkmcnt(0)
	s_barrier
	s_setprio 1
	s_waitcnt lgkmcnt(0)
	v_mfma_f32_16x16x32_bf16 v[62:65], v[130:133], v[162:165], v[62:65]
	v_mfma_f32_16x16x32_bf16 v[58:61], v[138:141], v[162:165], v[58:61]
	v_mfma_f32_16x16x32_bf16 v[46:49], v[130:133], v[170:173], v[46:49]
	v_mfma_f32_16x16x32_bf16 v[42:45], v[138:141], v[170:173], v[42:45]
	v_mfma_f32_16x16x32_bf16 v[30:33], v[130:133], v[178:181], v[30:33]
	v_mfma_f32_16x16x32_bf16 v[26:29], v[138:141], v[178:181], v[26:29]
	v_mfma_f32_16x16x32_bf16 v[14:17], v[130:133], v[186:189], v[14:17]
	v_mfma_f32_16x16x32_bf16 v[10:13], v[138:141], v[186:189], v[10:13]
	v_mfma_f32_16x16x32_bf16 v[62:65], v[134:137], v[166:169], v[62:65]
	v_mfma_f32_16x16x32_bf16 v[58:61], v[142:145], v[166:169], v[58:61]
	v_mfma_f32_16x16x32_bf16 v[46:49], v[134:137], v[174:177], v[46:49]
	v_mfma_f32_16x16x32_bf16 v[42:45], v[142:145], v[174:177], v[42:45]
	v_mfma_f32_16x16x32_bf16 v[30:33], v[134:137], v[182:185], v[30:33]
	v_mfma_f32_16x16x32_bf16 v[26:29], v[142:145], v[182:185], v[26:29]
	v_mfma_f32_16x16x32_bf16 v[14:17], v[134:137], v[190:193], v[14:17]
	v_mfma_f32_16x16x32_bf16 v[10:13], v[142:145], v[190:193], v[10:13]
	s_setprio 0
	s_setprio 1
	v_mfma_f32_16x16x32_bf16 v[54:57], v[146:149], v[162:165], v[54:57]
	v_mfma_f32_16x16x32_bf16 v[50:53], v[154:157], v[162:165], v[50:53]
	v_mfma_f32_16x16x32_bf16 v[38:41], v[146:149], v[170:173], v[38:41]
	v_mfma_f32_16x16x32_bf16 v[34:37], v[154:157], v[170:173], v[34:37]
	v_mfma_f32_16x16x32_bf16 v[22:25], v[146:149], v[178:181], v[22:25]
	v_mfma_f32_16x16x32_bf16 v[18:21], v[154:157], v[178:181], v[18:21]
	v_mfma_f32_16x16x32_bf16 v[6:9], v[146:149], v[186:189], v[6:9]
	v_mfma_f32_16x16x32_bf16 v[2:5], v[154:157], v[186:189], v[2:5]
	v_mfma_f32_16x16x32_bf16 v[54:57], v[150:153], v[166:169], v[54:57]
	v_mfma_f32_16x16x32_bf16 v[50:53], v[158:161], v[166:169], v[50:53]
	v_mfma_f32_16x16x32_bf16 v[38:41], v[150:153], v[174:177], v[38:41]
	v_mfma_f32_16x16x32_bf16 v[34:37], v[158:161], v[174:177], v[34:37]
	v_mfma_f32_16x16x32_bf16 v[22:25], v[150:153], v[182:185], v[22:25]
	v_mfma_f32_16x16x32_bf16 v[18:21], v[158:161], v[182:185], v[18:21]
	v_mfma_f32_16x16x32_bf16 v[6:9], v[150:153], v[190:193], v[6:9]
	v_mfma_f32_16x16x32_bf16 v[2:5], v[158:161], v[190:193], v[2:5]
	s_setprio 0
	s_barrier
	s_add_i32 s95, s95, 2
	s_add_u32 s12, s12, 0x100
	s_addc_u32 s13, s13, 0
	s_add_u32 s93, s93, 0x100
	s_addc_u32 s94, s94, 0
	s_cmp_gt_u32 s95, 13
	s_cbranch_scc0 .LBB0_713
	s_mov_b32 s98, 1
	s_and_b64 vcc, exec, s[28:29]
	s_cbranch_vccz .LBB0_716
	s_barrier

.LBB0_1182:
	s_mov_b32 s98, 0
	s_cmp_lt_i32 s34, 11
	s_cselect_b64 s[4:5], -1, 0
	s_and_b64 s[0:1], s[4:5], s[0:1]
	s_andn2_b64 vcc, exec, s[0:1]
	s_cbranch_vccnz .LBB0_1207
	s_cmpk_gt_i32 s2, 0x1ff
	v_readfirstlane_b32 s4, v0
	s_cbranch_scc1 .LBB0_1207
	s_ashr_i32 s3, s2, 31
	s_lshr_b32 s0, s3, 29
	s_add_i32 s7, s2, s0
	s_and_b32 s0, s7, -8
	s_sub_i32 s5, s2, s0
	s_cmp_gt_i32 s5, -1
	s_cbranch_scc0 .LBB0_1186
	s_lshl_b32 s6, s5, 6
	s_ashr_i32 s0, s7, 3
	s_cbranch_execz .LBB0_1187
	s_branch .LBB0_1188

.LBB0_1200:
	ds_read_b128 v[120:123], v207
	ds_read_b128 v[132:135], v207 offset:1024
	ds_read_b128 v[136:139], v207 offset:2048
	ds_read_b128 v[140:143], v207 offset:3072
	ds_read_b128 v[144:147], v208
	ds_read_b128 v[148:151], v208 offset:1024
	ds_read_b128 v[152:155], v208 offset:2048
	ds_read_b128 v[156:159], v208 offset:3072
	s_add_u32 s34, s28, 0xfffc0080
	s_addc_u32 s35, s29, -1
	s_cmp_eq_u32 s61, 12
	s_cselect_b32 s41, s21, s35
	s_cselect_b32 s40, s57, s34
	s_cselect_b32 s35, s19, s60
	s_cselect_b32 s34, s58, s59
	v_lshl_add_u64 v[222:223], s[28:29], 0, v[190:191]
	s_add_i32 m0, s45, 0xc000
	ds_read_b128 v[160:163], v209
	ds_read_b128 v[164:167], v209 offset:1024
	ds_read_b128 v[168:171], v209 offset:2048
	ds_read_b128 v[172:175], v209 offset:3072
	ds_read_b128 v[176:179], v209 offset:4096
	ds_read_b128 v[210:213], v209 offset:5120
	ds_read_b128 v[214:217], v209 offset:6144
	ds_read_b128 v[218:221], v209 offset:7168
	global_load_lds_dwordx4 v[222:223], off
	v_lshl_add_u64 v[222:223], s[28:29], 0, v[192:193]
	s_add_i32 m0, s45, 0xe000
	s_nop 0
	global_load_lds_dwordx4 v[222:223], off
	s_cmp_eq_u32 s98, 0
	s_cbranch_scc1 .Lrw_strict_p10_0
	s_waitcnt vmcnt(40)
	s_branch .Lrw_done_p10_0

.Lrw_done_p10_0:
	s_waitcnt lgkmcnt(0)
	s_barrier
	s_setprio 1
	s_waitcnt lgkmcnt(0)
	v_mfma_f32_16x16x32_bf16 v[128:131], v[120:123], v[160:163], v[128:131]
	v_mfma_f32_16x16x32_bf16 v[124:127], v[136:139], v[160:163], v[124:127]
	v_mfma_f32_16x16x32_bf16 v[108:111], v[120:123], v[168:171], v[108:111]
	v_mfma_f32_16x16x32_bf16 v[104:107], v[136:139], v[168:171], v[104:107]
	v_mfma_f32_16x16x32_bf16 v[92:95], v[120:123], v[176:179], v[92:95]
	v_mfma_f32_16x16x32_bf16 v[88:91], v[136:139], v[176:179], v[88:91]
	v_mfma_f32_16x16x32_bf16 v[76:79], v[120:123], v[214:217], v[76:79]
	v_mfma_f32_16x16x32_bf16 v[72:75], v[136:139], v[214:217], v[72:75]
	v_mfma_f32_16x16x32_bf16 v[128:131], v[132:135], v[164:167], v[128:131]
	v_mfma_f32_16x16x32_bf16 v[124:127], v[140:143], v[164:167], v[124:127]
	v_mfma_f32_16x16x32_bf16 v[108:111], v[132:135], v[172:175], v[108:111]
	v_mfma_f32_16x16x32_bf16 v[104:107], v[140:143], v[172:175], v[104:107]
	v_mfma_f32_16x16x32_bf16 v[92:95], v[132:135], v[210:213], v[92:95]
	v_mfma_f32_16x16x32_bf16 v[88:91], v[140:143], v[210:213], v[88:91]
	v_mfma_f32_16x16x32_bf16 v[76:79], v[132:135], v[218:221], v[76:79]
	v_mfma_f32_16x16x32_bf16 v[72:75], v[140:143], v[218:221], v[72:75]
	s_setprio 0
	s_setprio 1
	v_mfma_f32_16x16x32_bf16 v[116:119], v[144:147], v[160:163], v[116:119]
	v_mfma_f32_16x16x32_bf16 v[112:115], v[152:155], v[160:163], v[112:115]
	v_mfma_f32_16x16x32_bf16 v[100:103], v[144:147], v[168:171], v[100:103]
	v_mfma_f32_16x16x32_bf16 v[96:99], v[152:155], v[168:171], v[96:99]
	v_mfma_f32_16x16x32_bf16 v[84:87], v[144:147], v[176:179], v[84:87]
	v_mfma_f32_16x16x32_bf16 v[80:83], v[152:155], v[176:179], v[80:83]
	v_mfma_f32_16x16x32_bf16 v[68:71], v[144:147], v[214:217], v[68:71]
	v_mfma_f32_16x16x32_bf16 v[64:67], v[152:155], v[214:217], v[64:67]
	v_mfma_f32_16x16x32_bf16 v[116:119], v[148:151], v[164:167], v[116:119]
	v_mfma_f32_16x16x32_bf16 v[112:115], v[156:159], v[164:167], v[112:115]
	v_mfma_f32_16x16x32_bf16 v[100:103], v[148:151], v[172:175], v[100:103]
	v_mfma_f32_16x16x32_bf16 v[96:99], v[156:159], v[172:175], v[96:99]
	v_mfma_f32_16x16x32_bf16 v[84:87], v[148:151], v[210:213], v[84:87]
	v_mfma_f32_16x16x32_bf16 v[80:83], v[156:159], v[210:213], v[80:83]
	v_mfma_f32_16x16x32_bf16 v[68:71], v[148:151], v[218:221], v[68:71]
	v_mfma_f32_16x16x32_bf16 v[64:67], v[156:159], v[218:221], v[64:67]
	s_setprio 0
	s_barrier
	s_add_i32 s62, s53, s44
	v_lshl_add_u64 v[222:223], s[34:35], 0, v[182:183]
	s_mov_b32 m0, s62
	ds_read_b128 v[160:163], v209 offset:16384
	ds_read_b128 v[164:167], v209 offset:17408
	ds_read_b128 v[168:171], v209 offset:18432
	ds_read_b128 v[172:175], v209 offset:19456
	ds_read_b128 v[176:179], v209 offset:20480
	ds_read_b128 v[210:213], v209 offset:21504
	ds_read_b128 v[214:217], v209 offset:22528
	ds_read_b128 v[218:221], v209 offset:23552
	global_load_lds_dwordx4 v[222:223], off
	s_add_i32 m0, s62, 0x2000
	s_add_u32 s62, s34, 0x40000
	v_lshl_add_u64 v[224:225], s[34:35], 0, v[186:187]
	s_addc_u32 s63, s35, 0
	s_add_i32 s64, s54, s44
	global_load_lds_dwordx4 v[224:225], off
	v_lshl_add_u64 v[226:227], s[62:63], 0, v[182:183]
	s_mov_b32 m0, s64
	v_lshl_add_u64 v[228:229], s[40:41], 0, v[184:185]
	global_load_lds_dwordx4 v[226:227], off
	v_lshl_add_u64 v[226:227], s[62:63], 0, v[186:187]
	s_add_i32 m0, s64, 0x2000
	s_nop 0
	global_load_lds_dwordx4 v[226:227], off
	v_lshl_add_u64 v[226:227], s[40:41], 0, v[180:181]
	s_mov_b32 m0, s45
	s_nop 0
	global_load_lds_dwordx4 v[226:227], off
	s_mov_b32 m0, s46
	s_nop 0
	global_load_lds_dwordx4 v[228:229], off
	s_cmp_eq_u32 s98, 0
	s_cbranch_scc1 .Lrw_strict_p10_1
	s_waitcnt vmcnt(40)
	s_branch .Lrw_done_p10_1

.Lrw_done_p10_1:
	s_mov_b32 s98, 0
	s_waitcnt lgkmcnt(0)
	s_barrier
	s_setprio 1
	s_waitcnt lgkmcnt(0)
	v_mfma_f32_16x16x32_bf16 v[60:63], v[120:123], v[160:163], v[60:63]
	v_mfma_f32_16x16x32_bf16 v[56:59], v[136:139], v[160:163], v[56:59]
	v_mfma_f32_16x16x32_bf16 v[44:47], v[120:123], v[168:171], v[44:47]
	v_mfma_f32_16x16x32_bf16 v[40:43], v[136:139], v[168:171], v[40:43]
	v_mfma_f32_16x16x32_bf16 v[28:31], v[120:123], v[176:179], v[28:31]
	v_mfma_f32_16x16x32_bf16 v[24:27], v[136:139], v[176:179], v[24:27]
	v_mfma_f32_16x16x32_bf16 v[12:15], v[120:123], v[214:217], v[12:15]
	v_mfma_f32_16x16x32_bf16 v[8:11], v[136:139], v[214:217], v[8:11]
	v_mfma_f32_16x16x32_bf16 v[60:63], v[132:135], v[164:167], v[60:63]
	v_mfma_f32_16x16x32_bf16 v[56:59], v[140:143], v[164:167], v[56:59]
	v_mfma_f32_16x16x32_bf16 v[44:47], v[132:135], v[172:175], v[44:47]
	v_mfma_f32_16x16x32_bf16 v[40:43], v[140:143], v[172:175], v[40:43]
	v_mfma_f32_16x16x32_bf16 v[28:31], v[132:135], v[210:213], v[28:31]
	v_mfma_f32_16x16x32_bf16 v[24:27], v[140:143], v[210:213], v[24:27]
	v_mfma_f32_16x16x32_bf16 v[12:15], v[132:135], v[218:221], v[12:15]
	v_mfma_f32_16x16x32_bf16 v[8:11], v[140:143], v[218:221], v[8:11]
	s_setprio 0
	s_setprio 1
	v_mfma_f32_16x16x32_bf16 v[52:55], v[144:147], v[160:163], v[52:55]
	v_mfma_f32_16x16x32_bf16 v[48:51], v[152:155], v[160:163], v[48:51]
	v_mfma_f32_16x16x32_bf16 v[36:39], v[144:147], v[168:171], v[36:39]
	v_mfma_f32_16x16x32_bf16 v[32:35], v[152:155], v[168:171], v[32:35]
	v_mfma_f32_16x16x32_bf16 v[20:23], v[144:147], v[176:179], v[20:23]
	v_mfma_f32_16x16x32_bf16 v[16:19], v[152:155], v[176:179], v[16:19]
	v_mfma_f32_16x16x32_bf16 v[4:7], v[144:147], v[214:217], v[4:7]
	v_mfma_f32_16x16x32_bf16 v[0:3], v[152:155], v[214:217], v[0:3]
	v_mfma_f32_16x16x32_bf16 v[52:55], v[148:151], v[164:167], v[52:55]
	v_mfma_f32_16x16x32_bf16 v[48:51], v[156:159], v[164:167], v[48:51]
	v_mfma_f32_16x16x32_bf16 v[36:39], v[148:151], v[172:175], v[36:39]
	v_mfma_f32_16x16x32_bf16 v[32:35], v[156:159], v[172:175], v[32:35]
	v_mfma_f32_16x16x32_bf16 v[20:23], v[148:151], v[210:213], v[20:23]
	v_mfma_f32_16x16x32_bf16 v[16:19], v[156:159], v[210:213], v[16:19]
	v_mfma_f32_16x16x32_bf16 v[4:7], v[148:151], v[218:221], v[4:7]
	v_mfma_f32_16x16x32_bf16 v[0:3], v[156:159], v[218:221], v[0:3]
	s_setprio 0
	s_barrier
	s_add_i32 s62, 0, 0x18000
	s_add_i32 s63, 0, 0x1c000
	v_add_u32_e32 v140, s62, v201
	v_add_u32_e32 v156, s63, v201
	ds_read_b128 v[120:123], v140
	ds_read_b128 v[132:135], v140 offset:1024
	ds_read_b128 v[136:139], v140 offset:2048
	ds_read_b128 v[140:143], v140 offset:3072
	ds_read_b128 v[144:147], v156
	ds_read_b128 v[148:151], v156 offset:1024
	ds_read_b128 v[152:155], v156 offset:2048
	ds_read_b128 v[156:159], v156 offset:3072
	s_add_u32 s40, s40, 0x40000
	s_addc_u32 s41, s41, 0
	s_mov_b32 m0, s47
	v_lshl_add_u64 v[230:231], s[40:41], 0, v[180:181]
	ds_read_b128 v[160:163], v209 offset:32768
	ds_read_b128 v[164:167], v209 offset:33792
	ds_read_b128 v[168:171], v209 offset:34816
	ds_read_b128 v[172:175], v209 offset:35840
	ds_read_b128 v[176:179], v209 offset:36864
	ds_read_b128 v[210:213], v209 offset:37888
	ds_read_b128 v[214:217], v209 offset:38912
	ds_read_b128 v[218:221], v209 offset:39936
	global_load_lds_dwordx4 v[230:231], off
	v_lshl_add_u64 v[230:231], s[40:41], 0, v[184:185]
	s_mov_b32 m0, s48
	s_nop 0
	global_load_lds_dwordx4 v[230:231], off
	s_waitcnt vmcnt(8)
	s_waitcnt lgkmcnt(0)
	s_barrier
	s_setprio 1
	s_waitcnt lgkmcnt(0)
	v_mfma_f32_16x16x32_bf16 v[128:131], v[120:123], v[160:163], v[128:131]
	v_mfma_f32_16x16x32_bf16 v[124:127], v[136:139], v[160:163], v[124:127]
	v_mfma_f32_16x16x32_bf16 v[108:111], v[120:123], v[168:171], v[108:111]
	v_mfma_f32_16x16x32_bf16 v[104:107], v[136:139], v[168:171], v[104:107]
	v_mfma_f32_16x16x32_bf16 v[92:95], v[120:123], v[176:179], v[92:95]
	v_mfma_f32_16x16x32_bf16 v[88:91], v[136:139], v[176:179], v[88:91]
	v_mfma_f32_16x16x32_bf16 v[76:79], v[120:123], v[214:217], v[76:79]
	v_mfma_f32_16x16x32_bf16 v[72:75], v[136:139], v[214:217], v[72:75]
	v_mfma_f32_16x16x32_bf16 v[128:131], v[132:135], v[164:167], v[128:131]
	v_mfma_f32_16x16x32_bf16 v[124:127], v[140:143], v[164:167], v[124:127]
	v_mfma_f32_16x16x32_bf16 v[108:111], v[132:135], v[172:175], v[108:111]
	v_mfma_f32_16x16x32_bf16 v[104:107], v[140:143], v[172:175], v[104:107]
	v_mfma_f32_16x16x32_bf16 v[92:95], v[132:135], v[210:213], v[92:95]
	v_mfma_f32_16x16x32_bf16 v[88:91], v[140:143], v[210:213], v[88:91]
	v_mfma_f32_16x16x32_bf16 v[76:79], v[132:135], v[218:221], v[76:79]
	v_mfma_f32_16x16x32_bf16 v[72:75], v[140:143], v[218:221], v[72:75]
	s_setprio 0
	s_setprio 1
	v_mfma_f32_16x16x32_bf16 v[116:119], v[144:147], v[160:163], v[116:119]
	v_mfma_f32_16x16x32_bf16 v[112:115], v[152:155], v[160:163], v[112:115]
	v_mfma_f32_16x16x32_bf16 v[100:103], v[144:147], v[168:171], v[100:103]
	v_mfma_f32_16x16x32_bf16 v[96:99], v[152:155], v[168:171], v[96:99]
	v_mfma_f32_16x16x32_bf16 v[84:87], v[144:147], v[176:179], v[84:87]
	v_mfma_f32_16x16x32_bf16 v[80:83], v[152:155], v[176:179], v[80:83]
	v_mfma_f32_16x16x32_bf16 v[68:71], v[144:147], v[214:217], v[68:71]
	v_mfma_f32_16x16x32_bf16 v[64:67], v[152:155], v[214:217], v[64:67]
	v_mfma_f32_16x16x32_bf16 v[116:119], v[148:151], v[164:167], v[116:119]
	v_mfma_f32_16x16x32_bf16 v[112:115], v[156:159], v[164:167], v[112:115]
	v_mfma_f32_16x16x32_bf16 v[100:103], v[148:151], v[172:175], v[100:103]
	v_mfma_f32_16x16x32_bf16 v[96:99], v[156:159], v[172:175], v[96:99]
	v_mfma_f32_16x16x32_bf16 v[84:87], v[148:151], v[210:213], v[84:87]
	v_mfma_f32_16x16x32_bf16 v[80:83], v[156:159], v[210:213], v[80:83]
	v_mfma_f32_16x16x32_bf16 v[68:71], v[148:151], v[218:221], v[68:71]
	v_mfma_f32_16x16x32_bf16 v[64:67], v[156:159], v[218:221], v[64:67]
	s_setprio 0
	s_barrier
	s_add_i32 s40, s62, s44
	v_lshl_add_u64 v[222:223], v[222:223], 0, s[12:13]
	s_mov_b32 m0, s40
	ds_read_b128 v[160:163], v209 offset:49152
	ds_read_b128 v[164:167], v209 offset:50176
	ds_read_b128 v[168:171], v209 offset:51200
	ds_read_b128 v[172:175], v209 offset:52224
	ds_read_b128 v[176:179], v209 offset:53248
	ds_read_b128 v[210:213], v209 offset:54272
	ds_read_b128 v[214:217], v209 offset:55296
	ds_read_b128 v[218:221], v209 offset:56320
	global_load_lds_dwordx4 v[222:223], off
	s_add_i32 m0, s40, 0x2000
	s_add_u32 s34, s34, 0x40080
	v_lshl_add_u64 v[222:223], v[224:225], 0, s[12:13]
	s_addc_u32 s35, s35, 0
	s_add_i32 s40, s63, s44
	global_load_lds_dwordx4 v[222:223], off
	v_lshl_add_u64 v[222:223], s[34:35], 0, v[182:183]
	s_mov_b32 m0, s40
	s_nop 0
	global_load_lds_dwordx4 v[222:223], off
	v_lshl_add_u64 v[222:223], s[34:35], 0, v[186:187]
	s_add_i32 m0, s40, 0x2000
	s_nop 0
	global_load_lds_dwordx4 v[222:223], off
	v_lshl_add_u64 v[222:223], v[226:227], 0, s[12:13]
	s_mov_b32 m0, s49
	s_nop 0
	global_load_lds_dwordx4 v[222:223], off
	v_lshl_add_u64 v[222:223], v[228:229], 0, s[12:13]
	s_mov_b32 m0, s50
	s_nop 0
	global_load_lds_dwordx4 v[222:223], off
	s_waitcnt vmcnt(8)
	s_waitcnt lgkmcnt(0)
	s_barrier
	s_setprio 1
	s_waitcnt lgkmcnt(0)
	v_mfma_f32_16x16x32_bf16 v[60:63], v[120:123], v[160:163], v[60:63]
	v_mfma_f32_16x16x32_bf16 v[56:59], v[136:139], v[160:163], v[56:59]
	v_mfma_f32_16x16x32_bf16 v[44:47], v[120:123], v[168:171], v[44:47]
	v_mfma_f32_16x16x32_bf16 v[40:43], v[136:139], v[168:171], v[40:43]
	v_mfma_f32_16x16x32_bf16 v[28:31], v[120:123], v[176:179], v[28:31]
	v_mfma_f32_16x16x32_bf16 v[24:27], v[136:139], v[176:179], v[24:27]
	v_mfma_f32_16x16x32_bf16 v[12:15], v[120:123], v[214:217], v[12:15]
	v_mfma_f32_16x16x32_bf16 v[8:11], v[136:139], v[214:217], v[8:11]
	v_mfma_f32_16x16x32_bf16 v[60:63], v[132:135], v[164:167], v[60:63]
	v_mfma_f32_16x16x32_bf16 v[56:59], v[140:143], v[164:167], v[56:59]
	v_mfma_f32_16x16x32_bf16 v[44:47], v[132:135], v[172:175], v[44:47]
	v_mfma_f32_16x16x32_bf16 v[40:43], v[140:143], v[172:175], v[40:43]
	v_mfma_f32_16x16x32_bf16 v[28:31], v[132:135], v[210:213], v[28:31]
	v_mfma_f32_16x16x32_bf16 v[24:27], v[140:143], v[210:213], v[24:27]
	v_mfma_f32_16x16x32_bf16 v[12:15], v[132:135], v[218:221], v[12:15]
	v_mfma_f32_16x16x32_bf16 v[8:11], v[140:143], v[218:221], v[8:11]
	s_setprio 0
	s_setprio 1
	v_mfma_f32_16x16x32_bf16 v[52:55], v[144:147], v[160:163], v[52:55]
	v_mfma_f32_16x16x32_bf16 v[48:51], v[152:155], v[160:163], v[48:51]
	v_mfma_f32_16x16x32_bf16 v[36:39], v[144:147], v[168:171], v[36:39]
	v_mfma_f32_16x16x32_bf16 v[32:35], v[152:155], v[168:171], v[32:35]
	v_mfma_f32_16x16x32_bf16 v[20:23], v[144:147], v[176:179], v[20:23]
	v_mfma_f32_16x16x32_bf16 v[16:19], v[152:155], v[176:179], v[16:19]
	v_mfma_f32_16x16x32_bf16 v[4:7], v[144:147], v[214:217], v[4:7]
	v_mfma_f32_16x16x32_bf16 v[0:3], v[152:155], v[214:217], v[0:3]
	v_mfma_f32_16x16x32_bf16 v[52:55], v[148:151], v[164:167], v[52:55]
	v_mfma_f32_16x16x32_bf16 v[48:51], v[156:159], v[164:167], v[48:51]
	v_mfma_f32_16x16x32_bf16 v[36:39], v[148:151], v[172:175], v[36:39]
	v_mfma_f32_16x16x32_bf16 v[32:35], v[156:159], v[172:175], v[32:35]
	v_mfma_f32_16x16x32_bf16 v[20:23], v[148:151], v[210:213], v[20:23]
	v_mfma_f32_16x16x32_bf16 v[16:19], v[156:159], v[210:213], v[16:19]
	v_mfma_f32_16x16x32_bf16 v[4:7], v[148:151], v[218:221], v[4:7]
	v_mfma_f32_16x16x32_bf16 v[0:3], v[156:159], v[218:221], v[0:3]
	s_setprio 0
	s_barrier
	s_add_i32 s61, s61, 2
	s_add_u32 s28, s28, 0x100
	s_addc_u32 s29, s29, 0
	s_add_u32 s59, s59, 0x100
	s_addc_u32 s60, s60, 0
	s_cmp_gt_u32 s61, 13
	s_cbranch_scc0 .LBB0_1200
	s_mov_b32 s98, 1
	s_and_b64 vcc, exec, s[14:15]
	s_cbranch_vccz .LBB0_1203
	s_barrier

	.amdhsa_kernel _Z13hawk_moba_fwd4Args
		.amdhsa_group_segment_fixed_size 0
		.amdhsa_private_segment_fixed_size 0
		.amdhsa_kernarg_size 424
		.amdhsa_user_sgpr_count 2
		.amdhsa_user_sgpr_dispatch_ptr 0
		.amdhsa_user_sgpr_queue_ptr 0
		.amdhsa_user_sgpr_kernarg_segment_ptr 1
		.amdhsa_user_sgpr_dispatch_id 0
		.amdhsa_user_sgpr_kernarg_preload_length 0
		.amdhsa_user_sgpr_kernarg_preload_offset 0
		.amdhsa_user_sgpr_private_segment_size 0
		.amdhsa_uses_dynamic_stack 0
		.amdhsa_enable_private_segment 0
		.amdhsa_system_sgpr_workgroup_id_x 1
		.amdhsa_system_sgpr_workgroup_id_y 0
		.amdhsa_system_sgpr_workgroup_id_z 0
		.amdhsa_system_sgpr_workgroup_info 0
		.amdhsa_system_vgpr_workitem_id 0
		.amdhsa_next_free_vgpr 254
		.amdhsa_next_free_sgpr 100
		.amdhsa_accum_offset 256
		.amdhsa_reserve_vcc 1
		.amdhsa_float_round_mode_32 0
		.amdhsa_float_round_mode_16_64 0
		.amdhsa_float_denorm_mode_32 3
		.amdhsa_float_denorm_mode_16_64 3
		.amdhsa_dx10_clamp 1
		.amdhsa_ieee_mode 1
		.amdhsa_fp16_overflow 0
		.amdhsa_tg_split 0
		.amdhsa_exception_fp_ieee_invalid_op 0
		.amdhsa_exception_fp_denorm_src 0
		.amdhsa_exception_fp_ieee_div_zero 0
		.amdhsa_exception_fp_ieee_overflow 0
		.amdhsa_exception_fp_ieee_underflow 0
		.amdhsa_exception_fp_ieee_inexact 0
		.amdhsa_exception_int_div_zero 0
	.end_amdhsa_kernel

amdhsa.kernels:
  - .agpr_count:     0
    .args:
      - .offset:         0
        .size:           168
        .value_kind:     by_value
      - .offset:         168
        .size:           4
        .value_kind:     hidden_block_count_x
      - .offset:         172
        .size:           4
        .value_kind:     hidden_block_count_y
      - .offset:         176
        .size:           4
        .value_kind:     hidden_block_count_z
      - .offset:         180
        .size:           2
        .value_kind:     hidden_group_size_x
      - .offset:         182
        .size:           2
        .value_kind:     hidden_group_size_y
      - .offset:         184
        .size:           2
        .value_kind:     hidden_group_size_z
      - .offset:         186
        .size:           2
        .value_kind:     hidden_remainder_x
      - .offset:         188
        .size:           2
        .value_kind:     hidden_remainder_y
      - .offset:         190
        .size:           2
        .value_kind:     hidden_remainder_z
      - .offset:         208
        .size:           8
        .value_kind:     hidden_global_offset_x
      - .offset:         216
        .size:           8
        .value_kind:     hidden_global_offset_y
      - .offset:         224
        .size:           8
        .value_kind:     hidden_global_offset_z
      - .offset:         232
        .size:           2
        .value_kind:     hidden_grid_dims
      - .offset:         288
        .size:           4
        .value_kind:     hidden_dynamic_lds_size
    .group_segment_fixed_size: 0
    .kernarg_segment_align: 8
    .kernarg_segment_size: 424
    .language:       OpenCL C
    .language_version:
      - 2
      - 0
    .max_flat_workgroup_size: 512
    .name:           _Z13hawk_moba_fwd4Args
    .private_segment_fixed_size: 0
    .sgpr_count:     106
    .sgpr_spill_count: 0
    .symbol:         _Z13hawk_moba_fwd4Args.kd
    .uniform_work_group_size: 1
    .uses_dynamic_stack: false
    .vgpr_count:     254
    .vgpr_spill_count: 0
    .wavefront_size: 64
